# GEMM k-loops: wave priority raised from the barrier that publishes the LDS stage (fragment reads, next-step global loads, MFMAs) and lowered before the staging barrier
# speedup vs baseline: 1.0152x; 1.0063x over previous
; template <class Epi>
; __device__ __forceinline__ void gemm_tile64(const bf16_t* A, const bf16_t* Bt, int tm, int tn, const Epi& epi, char* smem, const float* ssq, int nparts) {
;     ...
;     auto sstore = [&](const Slab& sl) {
; #pragma unroll
;         for (int i = 0; i < 4; ++i) {
;             const int r = lrow + 32 * i;
;             *(u32x4*)(sA + r * 64 + ((lc8 ^ ((r >> 1) & 7)) * 8)) = sl.a[i];
;             const int rs = (r & 64) | (((r >> 2) & 3) << 4) | (((r >> 4) & 3) << 2) | (r & 3);
;             *(u32x4*)(sB + rs * 64 + ((lc8 ^ ((rs >> 1) & 7)) * 8)) = sl.b[i];
;         }
;     };
;     auto compute = [&]() {
; #pragma unroll
;         for (int ks = 0; ks < 2; ++ks) {
;             bf16x8 af[4], bfr[4];
; #pragma unroll
;             for (int m = 0; m < 4; ++m) { const int r = wr * 64 + m * 16 + fr; af[m] = *(const bf16x8*)(sA + r * 64 + (((ks * 4 + fq) ^ ((r >> 1) & 7)) * 8)); }
; #pragma unroll
;             for (int n = 0; n < 4; ++n) { const int r = wc * 64 + n * 16 + fr; bfr[n] = *(const bf16x8*)(sB + r * 64 + (((ks * 4 + fq) ^ ((r >> 1) & 7)) * 8)); }
; #pragma unroll
;             for (int m = 0; m < 4; ++m)
; #pragma unroll
;                 for (int n = 0; n < 4; ++n) acc[m][n] = __builtin_amdgcn_mfma_f32_16x16x32_bf16(bfr[n], af[m], acc[m][n], 0, 0, 0);
;         }
;     };
;     Slab s0;
;     gload(0, s0);
;     for (int kt = 0; kt < 16; ++kt) {
;         __syncthreads(); sstore(s0); __syncthreads();
;         gload(min(kt + 1, 15), s0);
;         compute();
.LBB0_51:
	s_waitcnt lgkmcnt(0)
	s_barrier
	s_waitcnt vmcnt(7)
	ds_write_b128 v100, v[64:67]
	s_waitcnt vmcnt(6)
	ds_write_b128 v101, v[68:71] offset:16384
	s_waitcnt vmcnt(5)
	ds_write_b128 v102, v[72:75]
	s_waitcnt vmcnt(4)
	ds_write_b128 v103, v[76:79] offset:16384
	s_waitcnt vmcnt(3)
	ds_write_b128 v104, v[156:159]
	s_waitcnt vmcnt(2)
	ds_write_b128 v105, v[160:163] offset:16384
	s_waitcnt vmcnt(1)
	ds_write_b128 v106, v[148:151]
	s_waitcnt vmcnt(0)
	ds_write_b128 v107, v[152:155] offset:16384
	s_add_i32 s13, s13, 1
	s_waitcnt lgkmcnt(0)
	s_barrier
	s_setprio 2
	ds_read_b128 v[80:83], v109 offset:16384
	ds_read_b128 v[84:87], v109 offset:18432
	ds_read_b128 v[88:91], v108
	ds_read_b128 v[92:95], v108 offset:2048
	ds_read_b128 v[116:119], v109 offset:20480
	ds_read_b128 v[120:123], v109 offset:22528
	s_cmp_eq_u32 s13, 17
	s_cbranch_scc1 .Lgs_nopf
	global_load_dwordx4 v[64:67], v135, s[98:99]
	global_load_dwordx4 v[68:71], v135, s[20:21]
	global_load_dwordx4 v[72:75], v136, s[98:99]
	global_load_dwordx4 v[76:79], v136, s[20:21]
	global_load_dwordx4 v[156:159], v137, s[98:99]
	global_load_dwordx4 v[160:163], v137, s[20:21]
	global_load_dwordx4 v[148:151], v138, s[98:99]
	global_load_dwordx4 v[152:155], v138, s[20:21]
	s_add_u32 s98, s98, 0x80
	s_addc_u32 s99, s99, 0
	s_add_u32 s20, s20, 0x80
	s_addc_u32 s21, s21, 0
.Lgs_nopf:
	s_waitcnt lgkmcnt(3)
	v_mfma_f32_16x16x32_bf16 v[60:63], v[80:83], v[88:91], v[60:63]
	v_mfma_f32_16x16x32_bf16 v[56:59], v[84:87], v[88:91], v[56:59]
	s_waitcnt lgkmcnt(1)
	v_mfma_f32_16x16x32_bf16 v[52:55], v[116:119], v[88:91], v[52:55]
	s_waitcnt lgkmcnt(0)
	v_mfma_f32_16x16x32_bf16 v[48:51], v[120:123], v[88:91], v[48:51]
	v_mfma_f32_16x16x32_bf16 v[44:47], v[80:83], v[92:95], v[44:47]
	v_mfma_f32_16x16x32_bf16 v[40:43], v[84:87], v[92:95], v[40:43]
	v_mfma_f32_16x16x32_bf16 v[36:39], v[116:119], v[92:95], v[36:39]
	v_mfma_f32_16x16x32_bf16 v[32:35], v[120:123], v[92:95], v[32:35]
	ds_read_b128 v[88:91], v108 offset:4096
	ds_read_b128 v[92:95], v108 offset:6144
	s_waitcnt lgkmcnt(1)
	v_mfma_f32_16x16x32_bf16 v[28:31], v[80:83], v[88:91], v[28:31]
	v_mfma_f32_16x16x32_bf16 v[24:27], v[84:87], v[88:91], v[24:27]
	v_mfma_f32_16x16x32_bf16 v[20:23], v[116:119], v[88:91], v[20:23]
	v_mfma_f32_16x16x32_bf16 v[12:15], v[120:123], v[88:91], v[12:15]
	s_waitcnt lgkmcnt(0)
	v_mfma_f32_16x16x32_bf16 v[0:3], v[80:83], v[92:95], v[0:3]
	v_mfma_f32_16x16x32_bf16 v[16:19], v[84:87], v[92:95], v[16:19]
	ds_read_b128 v[80:83], v111 offset:16384
	ds_read_b128 v[84:87], v111 offset:18432
	v_mfma_f32_16x16x32_bf16 v[8:11], v[116:119], v[92:95], v[8:11]
	v_mfma_f32_16x16x32_bf16 v[4:7], v[120:123], v[92:95], v[4:7]
	ds_read_b128 v[88:91], v110
	ds_read_b128 v[92:95], v110 offset:2048
	ds_read_b128 v[116:119], v111 offset:20480
	ds_read_b128 v[120:123], v111 offset:22528
	s_waitcnt lgkmcnt(3)
	v_mfma_f32_16x16x32_bf16 v[60:63], v[80:83], v[88:91], v[60:63]
	v_mfma_f32_16x16x32_bf16 v[56:59], v[84:87], v[88:91], v[56:59]
	s_waitcnt lgkmcnt(1)
	v_mfma_f32_16x16x32_bf16 v[52:55], v[116:119], v[88:91], v[52:55]
	s_waitcnt lgkmcnt(0)
	v_mfma_f32_16x16x32_bf16 v[48:51], v[120:123], v[88:91], v[48:51]
	ds_read_b128 v[88:91], v110 offset:4096
	ds_read_b128 v[144:147], v110 offset:6144
	v_mfma_f32_16x16x32_bf16 v[44:47], v[80:83], v[92:95], v[44:47]
	v_mfma_f32_16x16x32_bf16 v[40:43], v[84:87], v[92:95], v[40:43]
	v_mfma_f32_16x16x32_bf16 v[36:39], v[116:119], v[92:95], v[36:39]
	v_mfma_f32_16x16x32_bf16 v[32:35], v[120:123], v[92:95], v[32:35]
	s_waitcnt lgkmcnt(1)
	v_mfma_f32_16x16x32_bf16 v[28:31], v[80:83], v[88:91], v[28:31]
	v_mfma_f32_16x16x32_bf16 v[24:27], v[84:87], v[88:91], v[24:27]
	v_mfma_f32_16x16x32_bf16 v[20:23], v[116:119], v[88:91], v[20:23]
	v_mfma_f32_16x16x32_bf16 v[12:15], v[120:123], v[88:91], v[12:15]
	s_waitcnt lgkmcnt(0)
	v_mfma_f32_16x16x32_bf16 v[0:3], v[80:83], v[144:147], v[0:3]
	v_mfma_f32_16x16x32_bf16 v[16:19], v[84:87], v[144:147], v[16:19]
	v_mfma_f32_16x16x32_bf16 v[8:11], v[116:119], v[144:147], v[8:11]
	v_mfma_f32_16x16x32_bf16 v[4:7], v[120:123], v[144:147], v[4:7]
	s_setprio 0
	s_cmp_eq_u32 s13, 17
	s_cbranch_scc0 .LBB0_51
	s_mov_b32 s21, 0
	s_movk_i32 s20, 0x780
	s_mov_b32 s14, 15
	v_lshl_or_b32 v64, v97, 6, v96
	v_lshlrev_b32_e32 v67, 2, v64
	ds_read_b32 v66, v67 offset:32768
	v_or3_b32 v65, v98, s22, v99
	v_cmp_eq_u32_e32 vcc, 0, v65
	s_lshl_b32 s13, s12, 9
	v_ashrrev_i32_e32 v65, 31, v64
	s_and_saveexec_b64 s[24:25], vcc
	s_cbranch_execz .LBB0_54
	v_readlane_b32 s36, v165, 42
	v_readlane_b32 s40, v165, 46
	v_readlane_b32 s41, v165, 47
	s_add_u32 s14, s40, s13
	s_addc_u32 s15, s41, 0
	v_lshl_add_u64 v[68:69], v[64:65], 2, s[14:15]
	v_readlane_b32 s37, v165, 43
	v_readlane_b32 s38, v165, 44
	v_readlane_b32 s39, v165, 45
	v_readlane_b32 s42, v165, 48
	v_readlane_b32 s43, v165, 49
	v_readlane_b32 s44, v165, 50
	v_readlane_b32 s45, v165, 51
	v_readlane_b32 s46, v165, 52
	v_readlane_b32 s47, v165, 53
	v_readlane_b32 s48, v165, 54
	v_readlane_b32 s49, v165, 55
	v_readlane_b32 s50, v165, 56
	v_readlane_b32 s51, v165, 57
	s_waitcnt lgkmcnt(0)
	global_store_dword v[68:69], v66, off

; template <class Epi>
; __device__ __forceinline__ void gemm_tile64(const bf16_t* A, const bf16_t* Bt, int tm, int tn, const Epi& epi, char* smem, const float* ssq, int nparts) {
;     ...
;     auto sstore = [&](const Slab& sl) {
; #pragma unroll
;         for (int i = 0; i < 4; ++i) {
;             const int r = lrow + 32 * i;
;             *(u32x4*)(sA + r * 64 + ((lc8 ^ ((r >> 1) & 7)) * 8)) = sl.a[i];
;             const int rs = (r & 64) | (((r >> 2) & 3) << 4) | (((r >> 4) & 3) << 2) | (r & 3);
;             *(u32x4*)(sB + rs * 64 + ((lc8 ^ ((rs >> 1) & 7)) * 8)) = sl.b[i];
;         }
;     };
;     auto compute = [&]() {
; #pragma unroll
;         for (int ks = 0; ks < 2; ++ks) {
;             bf16x8 af[4], bfr[4];
; #pragma unroll
;             for (int m = 0; m < 4; ++m) { const int r = wr * 64 + m * 16 + fr; af[m] = *(const bf16x8*)(sA + r * 64 + (((ks * 4 + fq) ^ ((r >> 1) & 7)) * 8)); }
; #pragma unroll
;             for (int n = 0; n < 4; ++n) { const int r = wc * 64 + n * 16 + fr; bfr[n] = *(const bf16x8*)(sB + r * 64 + (((ks * 4 + fq) ^ ((r >> 1) & 7)) * 8)); }
; #pragma unroll
;             for (int m = 0; m < 4; ++m)
; #pragma unroll
;                 for (int n = 0; n < 4; ++n) acc[m][n] = __builtin_amdgcn_mfma_f32_16x16x32_bf16(bfr[n], af[m], acc[m][n], 0, 0, 0);
;         }
;     };
;     Slab s0;
;     gload(0, s0);
;     for (int kt = 0; kt < 16; ++kt) {
;         __syncthreads(); sstore(s0); __syncthreads();
;         gload(min(kt + 1, 15), s0);
;         compute();
.LBB0_71:
	s_waitcnt lgkmcnt(0)
	s_barrier
	s_waitcnt vmcnt(7)
	ds_write_b128 v100, v[64:67]
	s_waitcnt vmcnt(6)
	ds_write_b128 v101, v[68:71] offset:16384
	s_waitcnt vmcnt(5)
	ds_write_b128 v102, v[72:75]
	s_waitcnt vmcnt(4)
	ds_write_b128 v103, v[76:79] offset:16384
	s_waitcnt vmcnt(3)
	ds_write_b128 v104, v[156:159]
	s_waitcnt vmcnt(2)
	ds_write_b128 v105, v[160:163] offset:16384
	s_waitcnt vmcnt(1)
	ds_write_b128 v106, v[148:151]
	s_waitcnt vmcnt(0)
	ds_write_b128 v107, v[152:155] offset:16384
	s_add_i32 s1, s1, 1
	s_waitcnt lgkmcnt(0)
	s_barrier
	s_setprio 2
	ds_read_b128 v[80:83], v109 offset:16384
	ds_read_b128 v[84:87], v109 offset:18432
	ds_read_b128 v[88:91], v108
	ds_read_b128 v[92:95], v108 offset:2048
	ds_read_b128 v[116:119], v109 offset:20480
	ds_read_b128 v[120:123], v109 offset:22528
	s_cmp_eq_u32 s1, 17
	s_cbranch_scc1 .Lgo_nopf
	global_load_dwordx4 v[64:67], v135, s[98:99]
	global_load_dwordx4 v[68:71], v135, s[20:21]
	global_load_dwordx4 v[72:75], v136, s[98:99]
	global_load_dwordx4 v[76:79], v136, s[20:21]
	global_load_dwordx4 v[156:159], v137, s[98:99]
	global_load_dwordx4 v[160:163], v137, s[20:21]
	global_load_dwordx4 v[148:151], v138, s[98:99]
	global_load_dwordx4 v[152:155], v138, s[20:21]
	s_add_u32 s98, s98, 0x80
	s_addc_u32 s99, s99, 0
	s_add_u32 s20, s20, 0x80
	s_addc_u32 s21, s21, 0
.Lgo_nopf:
	s_waitcnt lgkmcnt(3)
	v_mfma_f32_16x16x32_bf16 v[60:63], v[80:83], v[88:91], v[60:63]
	v_mfma_f32_16x16x32_bf16 v[56:59], v[84:87], v[88:91], v[56:59]
	s_waitcnt lgkmcnt(1)
	v_mfma_f32_16x16x32_bf16 v[52:55], v[116:119], v[88:91], v[52:55]
	s_waitcnt lgkmcnt(0)
	v_mfma_f32_16x16x32_bf16 v[48:51], v[120:123], v[88:91], v[48:51]
	v_mfma_f32_16x16x32_bf16 v[44:47], v[80:83], v[92:95], v[44:47]
	v_mfma_f32_16x16x32_bf16 v[40:43], v[84:87], v[92:95], v[40:43]
	v_mfma_f32_16x16x32_bf16 v[36:39], v[116:119], v[92:95], v[36:39]
	v_mfma_f32_16x16x32_bf16 v[32:35], v[120:123], v[92:95], v[32:35]
	ds_read_b128 v[88:91], v108 offset:4096
	ds_read_b128 v[92:95], v108 offset:6144
	s_waitcnt lgkmcnt(1)
	v_mfma_f32_16x16x32_bf16 v[28:31], v[80:83], v[88:91], v[28:31]
	v_mfma_f32_16x16x32_bf16 v[24:27], v[84:87], v[88:91], v[24:27]
	v_mfma_f32_16x16x32_bf16 v[20:23], v[116:119], v[88:91], v[20:23]
	v_mfma_f32_16x16x32_bf16 v[16:19], v[120:123], v[88:91], v[16:19]
	s_waitcnt lgkmcnt(0)
	v_mfma_f32_16x16x32_bf16 v[4:7], v[80:83], v[92:95], v[4:7]
	v_mfma_f32_16x16x32_bf16 v[12:15], v[84:87], v[92:95], v[12:15]
	ds_read_b128 v[80:83], v111 offset:16384
	ds_read_b128 v[84:87], v111 offset:18432
	v_mfma_f32_16x16x32_bf16 v[8:11], v[116:119], v[92:95], v[8:11]
	v_mfma_f32_16x16x32_bf16 v[0:3], v[120:123], v[92:95], v[0:3]
	ds_read_b128 v[88:91], v110
	ds_read_b128 v[92:95], v110 offset:2048
	ds_read_b128 v[116:119], v111 offset:20480
	ds_read_b128 v[120:123], v111 offset:22528
	s_waitcnt lgkmcnt(3)
	v_mfma_f32_16x16x32_bf16 v[60:63], v[80:83], v[88:91], v[60:63]
	v_mfma_f32_16x16x32_bf16 v[56:59], v[84:87], v[88:91], v[56:59]
	s_waitcnt lgkmcnt(1)
	v_mfma_f32_16x16x32_bf16 v[52:55], v[116:119], v[88:91], v[52:55]
	s_waitcnt lgkmcnt(0)
	v_mfma_f32_16x16x32_bf16 v[48:51], v[120:123], v[88:91], v[48:51]
	ds_read_b128 v[88:91], v110 offset:4096
	ds_read_b128 v[144:147], v110 offset:6144
	v_mfma_f32_16x16x32_bf16 v[44:47], v[80:83], v[92:95], v[44:47]
	v_mfma_f32_16x16x32_bf16 v[40:43], v[84:87], v[92:95], v[40:43]
	v_mfma_f32_16x16x32_bf16 v[36:39], v[116:119], v[92:95], v[36:39]
	v_mfma_f32_16x16x32_bf16 v[32:35], v[120:123], v[92:95], v[32:35]
	s_waitcnt lgkmcnt(1)
	v_mfma_f32_16x16x32_bf16 v[28:31], v[80:83], v[88:91], v[28:31]
	v_mfma_f32_16x16x32_bf16 v[24:27], v[84:87], v[88:91], v[24:27]
	v_mfma_f32_16x16x32_bf16 v[20:23], v[116:119], v[88:91], v[20:23]
	v_mfma_f32_16x16x32_bf16 v[16:19], v[120:123], v[88:91], v[16:19]
	s_waitcnt lgkmcnt(0)
	v_mfma_f32_16x16x32_bf16 v[4:7], v[80:83], v[144:147], v[4:7]
	v_mfma_f32_16x16x32_bf16 v[12:15], v[84:87], v[144:147], v[12:15]
	v_mfma_f32_16x16x32_bf16 v[8:11], v[116:119], v[144:147], v[8:11]
	v_mfma_f32_16x16x32_bf16 v[0:3], v[120:123], v[144:147], v[0:3]
	s_setprio 0
	s_cmp_eq_u32 s1, 17
	s_cbranch_scc0 .LBB0_71
; __device__ __forceinline__ unsigned pk_bf16(float lo, float hi) { unsigned r; asm("v_cvt_pk_bf16_f32 %0, %1, %2" : "=v"(r) : "v"(lo), "v"(hi)); return r; }
;     __device__ __forceinline__ void operator()(const f32x4 (&acc)[4][4], int tm, int tn, int wr, int wc, int fr, int fq, const float*) const {
;         const int col0 = tn * 128 + wc * 64 + fq * 16;
; #pragma unroll
;         for (int m = 0; m < 4; ++m) {
;             const size_t row = (size_t)tm * 128 + wr * 64 + m * 16 + fr;
;             f32x4 o[4]; float sq = 0.f;
; #pragma unroll
;             for (int n = 0; n < 4; ++n) {
;                 o[n] = *(const f32x4*)(xin + row * 1024 + col0 + n * 4) + acc[m][n];
;                 *(f32x4*)(xout + row * 1024 + col0 + n * 4) = o[n];
;                 sq += o[n][0] * o[n][0] + o[n][1] * o[n][1] + o[n][2] * o[n][2] + o[n][3] * o[n][3];
;             }
;             u32x4 w0, w1;
;             w0.x = pk_bf16(o[0][0], o[0][1]); w0.y = pk_bf16(o[0][2], o[0][3]); w0.z = pk_bf16(o[1][0], o[1][1]); w0.w = pk_bf16(o[1][2], o[1][3]);
;             w1.x = pk_bf16(o[2][0], o[2][1]); w1.y = pk_bf16(o[2][2], o[2][3]); w1.z = pk_bf16(o[3][0], o[3][1]); w1.w = pk_bf16(o[3][2], o[3][3]);
;             *(u32x4*)(xb + row * 1024 + col0) = w0; *(u32x4*)(xb + row * 1024 + col0 + 8) = w1;
;             sq += __shfl_xor(sq, 16); sq += __shfl_xor(sq, 32);
;             if (fq == 0) ssq[(size_t)(tn * 2 + wc) * T + row] = sq;
	s_mov_b32 s21, 0
	s_movk_i32 s20, 0x780
	s_mov_b32 s13, 15
	v_lshlrev_b32_e32 v66, 6, v99
	s_lshl_b32 s20, s12, 7
	v_ashrrev_i32_e32 v67, 31, v66
	s_lshl_b32 s1, s0, 7
	v_lshlrev_b32_e32 v64, 6, v96
	v_lshlrev_b32_e32 v65, 4, v97
	v_lshl_add_u64 v[66:67], s[20:21], 0, v[66:67]
	v_or3_b32 v64, v64, s1, v65
	v_or_b32_e32 v66, v66, v98
	v_lshl_or_b32 v68, s0, 1, v96
	v_ashrrev_i32_e32 v65, 31, v64
	v_ashrrev_i32_e32 v69, 31, v68
	v_lshlrev_b64 v[76:77], 12, v[66:67]
	v_lshlrev_b64 v[70:71], 17, v[68:69]
	v_lshl_add_u64 v[72:73], s[22:23], 0, v[76:77]
	v_lshlrev_b64 v[68:69], 2, v[64:65]
	v_lshl_add_u64 v[78:79], v[72:73], 0, v[68:69]
	global_load_dwordx4 v[82:85], v[78:79], off
	global_load_dwordx4 v[86:89], v[78:79], off offset:16
	global_load_dwordx4 v[90:93], v[78:79], off offset:32
	global_load_dwordx4 v[116:119], v[78:79], off offset:48
	v_add_co_u32_e32 v94, vcc, 0x10000, v78
	s_nop 1
	v_addc_co_u32_e32 v95, vcc, 0, v79, vcc
	global_load_dwordx4 v[120:123], v[94:95], off
	global_load_dwordx4 v[144:147], v[94:95], off offset:16
	global_load_dwordx4 v[148:151], v[94:95], off offset:32
	global_load_dwordx4 v[152:155], v[94:95], off offset:48
	v_add_co_u32_e32 v94, vcc, 0x20000, v78
	s_nop 1
	v_addc_co_u32_e32 v95, vcc, 0, v79, vcc
	global_load_dwordx4 v[156:159], v[94:95], off
	global_load_dwordx4 v[160:163], v[94:95], off offset:16
	global_load_dwordx4 v[100:103], v[94:95], off offset:32
	global_load_dwordx4 v[104:107], v[94:95], off offset:48
	v_add_co_u32_e32 v94, vcc, 0x30000, v78
	s_nop 1
	v_addc_co_u32_e32 v95, vcc, 0, v79, vcc
	global_load_dwordx4 v[108:111], v[94:95], off
	global_load_dwordx4 v[136:139], v[94:95], off offset:16
	global_load_dwordx4 v[140:143], v[94:95], off offset:32
	global_load_dwordx4 v[112:115], v[94:95], off offset:48
	v_readlane_b32 s36, v165, 42
	v_readlane_b32 s46, v165, 52
	v_readlane_b32 s47, v165, 53
	v_cmp_lt_i32_e64 s[0:1], v134, v132
	v_readlane_b32 s50, v165, 56
	v_readlane_b32 s51, v165, 57
	v_cmp_eq_u32_e32 vcc, 0, v97
	v_readlane_b32 s37, v165, 43
	v_readlane_b32 s38, v165, 44
	v_readlane_b32 s39, v165, 45
	v_readlane_b32 s40, v165, 46
	v_readlane_b32 s41, v165, 47
	v_readlane_b32 s42, v165, 48
	v_readlane_b32 s43, v165, 49
	v_readlane_b32 s44, v165, 50
	v_readlane_b32 s45, v165, 51
	v_readlane_b32 s48, v165, 54
	v_readlane_b32 s49, v165, 55
	s_waitcnt vmcnt(0)
	v_pk_add_f32 v[60:61], v[60:61], v[82:83]
	v_lshl_add_u64 v[72:73], s[82:83], 0, v[76:77]
	v_pk_add_f32 v[62:63], v[62:63], v[84:85]
	v_lshl_add_u64 v[76:77], v[72:73], 0, v[68:69]
	global_store_dwordx4 v[76:77], v[60:63], off
	v_mul_f32_e32 v80, v61, v61
	v_fmac_f32_e32 v80, v60, v60
	v_fmac_f32_e32 v80, v62, v62
	v_fmac_f32_e32 v80, v63, v63
	v_cvt_pk_bf16_f32 v60, v60, v61
	v_cvt_pk_bf16_f32 v61, v62, v63
	v_pk_add_f32 v[56:57], v[56:57], v[86:87]
	s_nop 0
	v_mul_f32_e32 v72, v57, v57
	v_pk_add_f32 v[58:59], v[58:59], v[88:89]
	v_fmac_f32_e32 v72, v56, v56
	v_fmac_f32_e32 v72, v58, v58
	global_store_dwordx4 v[76:77], v[56:59], off offset:16
	v_fmac_f32_e32 v72, v59, v59
	v_add_f32_e32 v80, v80, v72
	v_cvt_pk_bf16_f32 v62, v56, v57
	v_cvt_pk_bf16_f32 v63, v58, v59
	v_pk_add_f32 v[52:53], v[52:53], v[90:91]
	s_nop 0
	v_mul_f32_e32 v72, v53, v53
	v_pk_add_f32 v[54:55], v[54:55], v[92:93]
	v_fmac_f32_e32 v72, v52, v52
	v_fmac_f32_e32 v72, v54, v54
	global_store_dwordx4 v[76:77], v[52:55], off offset:32
	v_fmac_f32_e32 v72, v55, v55
	v_add_f32_e32 v80, v80, v72
	v_cvt_pk_bf16_f32 v52, v52, v53
	v_cvt_pk_bf16_f32 v53, v54, v55
	v_pk_add_f32 v[48:49], v[48:49], v[116:117]
	v_pk_add_f32 v[50:51], v[50:51], v[118:119]
	v_mul_f32_e32 v72, v49, v49
	global_store_dwordx4 v[76:77], v[48:51], off offset:48
	v_fmac_f32_e32 v72, v48, v48
	v_cvt_pk_bf16_f32 v54, v48, v49
	v_fmac_f32_e32 v72, v50, v50
	v_lshlrev_b64 v[48:49], 11, v[66:67]
	v_lshl_add_u64 v[48:49], s[46:47], 0, v[48:49]
	v_lshl_add_u64 v[48:49], v[64:65], 1, v[48:49]
	v_fmac_f32_e32 v72, v51, v51
	v_cvt_pk_bf16_f32 v55, v50, v51
	global_store_dwordx4 v[48:49], v[60:63], off
	global_store_dwordx4 v[48:49], v[52:55], off offset:16
	v_cndmask_b32_e64 v48, v130, v134, s[0:1]
	v_add_f32_e32 v72, v80, v72
	v_lshlrev_b32_e32 v50, 2, v48
	ds_bpermute_b32 v48, v50, v72
	v_cmp_lt_i32_e64 s[0:1], v133, v132
	s_waitcnt lgkmcnt(0)
	v_add_f32_e32 v52, v72, v48
	v_cndmask_b32_e64 v48, v130, v133, s[0:1]
	v_lshlrev_b32_e32 v51, 2, v48
	ds_bpermute_b32 v53, v51, v52
	v_lshl_add_u64 v[48:49], s[50:51], 0, v[70:71]
	v_lshl_add_u64 v[48:49], v[66:67], 2, v[48:49]
	s_and_saveexec_b64 s[0:1], vcc
	s_cbranch_execz .LBB0_74
	s_waitcnt lgkmcnt(0)
	v_add_f32_e32 v52, v52, v53
	global_store_dword v[48:49], v52, off

; template <class Epi>
; __device__ __forceinline__ void gemm_tile64(const bf16_t* A, const bf16_t* Bt, int tm, int tn, const Epi& epi, char* smem, const float* ssq, int nparts) {
;     ...
;     auto sstore = [&](const Slab& sl) {
; #pragma unroll
;         for (int i = 0; i < 4; ++i) {
;             const int r = lrow + 32 * i;
;             *(u32x4*)(sA + r * 64 + ((lc8 ^ ((r >> 1) & 7)) * 8)) = sl.a[i];
;             const int rs = (r & 64) | (((r >> 2) & 3) << 4) | (((r >> 4) & 3) << 2) | (r & 3);
;             *(u32x4*)(sB + rs * 64 + ((lc8 ^ ((rs >> 1) & 7)) * 8)) = sl.b[i];
;         }
;     };
;     ...
;     for (int kt = 0; kt < 16; ++kt) {
;         __syncthreads(); sstore(s0); __syncthreads();
;         gload(min(kt + 1, 15), s0);
;         compute();
.LBB0_376:
	s_waitcnt lgkmcnt(0)
	s_barrier
	s_waitcnt vmcnt(7)
	ds_write_b128 v100, v[64:67]
	s_waitcnt vmcnt(6)
	ds_write_b128 v101, v[68:71] offset:16384
	s_waitcnt vmcnt(5)
	ds_write_b128 v102, v[72:75]
	s_waitcnt vmcnt(4)
	ds_write_b128 v103, v[76:79] offset:16384
	s_waitcnt vmcnt(3)
	ds_write_b128 v104, v[156:159]
	s_waitcnt vmcnt(2)
	ds_write_b128 v105, v[160:163] offset:16384
	s_waitcnt vmcnt(1)
	ds_write_b128 v106, v[148:151]
	s_waitcnt vmcnt(0)
	ds_write_b128 v107, v[152:155] offset:16384
	s_add_i32 s0, s0, 1
	s_waitcnt lgkmcnt(0)
	s_barrier
	s_setprio 2
	ds_read_b128 v[80:83], v109 offset:16384
	ds_read_b128 v[84:87], v109 offset:18432
	ds_read_b128 v[88:91], v108
	ds_read_b128 v[92:95], v108 offset:2048
	ds_read_b128 v[116:119], v109 offset:20480
	ds_read_b128 v[120:123], v109 offset:22528
	s_cmp_eq_u32 s0, 17
	s_cbranch_scc1 .Lgi_nopf
	global_load_dwordx4 v[64:67], v135, s[98:99]
	global_load_dwordx4 v[68:71], v135, s[20:21]
	global_load_dwordx4 v[72:75], v136, s[98:99]
	global_load_dwordx4 v[76:79], v136, s[20:21]
	global_load_dwordx4 v[156:159], v137, s[98:99]
	global_load_dwordx4 v[160:163], v137, s[20:21]
	global_load_dwordx4 v[148:151], v138, s[98:99]
	global_load_dwordx4 v[152:155], v138, s[20:21]
	s_add_u32 s98, s98, 0x80
	s_addc_u32 s99, s99, 0
	s_add_u32 s20, s20, 0x80
	s_addc_u32 s21, s21, 0
; template <class Epi>
; __device__ __forceinline__ void gemm_tile64(const bf16_t* A, const bf16_t* Bt, int tm, int tn, const Epi& epi, char* smem, const float* ssq, int nparts) {
;     ...
;         for (int ks = 0; ks < 2; ++ks) {
;             bf16x8 af[4], bfr[4];
; #pragma unroll
;             for (int m = 0; m < 4; ++m) { const int r = wr * 64 + m * 16 + fr; af[m] = *(const bf16x8*)(sA + r * 64 + (((ks * 4 + fq) ^ ((r >> 1) & 7)) * 8)); }
; #pragma unroll
;             for (int n = 0; n < 4; ++n) { const int r = wc * 64 + n * 16 + fr; bfr[n] = *(const bf16x8*)(sB + r * 64 + (((ks * 4 + fq) ^ ((r >> 1) & 7)) * 8)); }
; #pragma unroll
;             for (int m = 0; m < 4; ++m)
; #pragma unroll
;                 for (int n = 0; n < 4; ++n) acc[m][n] = __builtin_amdgcn_mfma_f32_16x16x32_bf16(bfr[n], af[m], acc[m][n], 0, 0, 0);
;     __device__ __forceinline__ void operator()(const f32x4 (&acc)[4][4], int tm, int tn, int wr, int wc, int fr, int fq, const float* sRs) const {
;         const int col0 = tn * 128 + wc * 64 + fq * 16;
; #pragma unroll
;         for (int m = 0; m < 4; ++m) {
;             const int rl = wr * 64 + m * 16 + fr; const float rs = sRs[rl]; const size_t row = (size_t)tm * 128 + rl;
.Lgi_nopf:
	s_waitcnt lgkmcnt(3)
	v_mfma_f32_16x16x32_bf16 v[60:63], v[80:83], v[88:91], v[60:63]
	v_mfma_f32_16x16x32_bf16 v[56:59], v[84:87], v[88:91], v[56:59]
	s_waitcnt lgkmcnt(1)
	v_mfma_f32_16x16x32_bf16 v[52:55], v[116:119], v[88:91], v[52:55]
	s_waitcnt lgkmcnt(0)
	v_mfma_f32_16x16x32_bf16 v[48:51], v[120:123], v[88:91], v[48:51]
	v_mfma_f32_16x16x32_bf16 v[44:47], v[80:83], v[92:95], v[44:47]
	v_mfma_f32_16x16x32_bf16 v[40:43], v[84:87], v[92:95], v[40:43]
	v_mfma_f32_16x16x32_bf16 v[36:39], v[116:119], v[92:95], v[36:39]
	v_mfma_f32_16x16x32_bf16 v[32:35], v[120:123], v[92:95], v[32:35]
	ds_read_b128 v[88:91], v108 offset:4096
	ds_read_b128 v[92:95], v108 offset:6144
	s_waitcnt lgkmcnt(1)
	v_mfma_f32_16x16x32_bf16 v[28:31], v[80:83], v[88:91], v[28:31]
	v_mfma_f32_16x16x32_bf16 v[24:27], v[84:87], v[88:91], v[24:27]
	v_mfma_f32_16x16x32_bf16 v[16:19], v[116:119], v[88:91], v[16:19]
	v_mfma_f32_16x16x32_bf16 v[12:15], v[120:123], v[88:91], v[12:15]
	s_waitcnt lgkmcnt(0)
	v_mfma_f32_16x16x32_bf16 v[8:11], v[80:83], v[92:95], v[8:11]
	v_mfma_f32_16x16x32_bf16 v[20:23], v[84:87], v[92:95], v[20:23]
	ds_read_b128 v[80:83], v111 offset:16384
	ds_read_b128 v[84:87], v111 offset:18432
	v_mfma_f32_16x16x32_bf16 v[4:7], v[116:119], v[92:95], v[4:7]
	v_mfma_f32_16x16x32_bf16 v[0:3], v[120:123], v[92:95], v[0:3]
	ds_read_b128 v[88:91], v110
	ds_read_b128 v[92:95], v110 offset:2048
	ds_read_b128 v[116:119], v111 offset:20480
	ds_read_b128 v[120:123], v111 offset:22528
	s_waitcnt lgkmcnt(3)
	v_mfma_f32_16x16x32_bf16 v[60:63], v[80:83], v[88:91], v[60:63]
	v_mfma_f32_16x16x32_bf16 v[56:59], v[84:87], v[88:91], v[56:59]
	s_waitcnt lgkmcnt(1)
	v_mfma_f32_16x16x32_bf16 v[52:55], v[116:119], v[88:91], v[52:55]
	s_waitcnt lgkmcnt(0)
	v_mfma_f32_16x16x32_bf16 v[48:51], v[120:123], v[88:91], v[48:51]
	ds_read_b128 v[88:91], v110 offset:4096
	ds_read_b128 v[144:147], v110 offset:6144
	v_mfma_f32_16x16x32_bf16 v[44:47], v[80:83], v[92:95], v[44:47]
	v_mfma_f32_16x16x32_bf16 v[40:43], v[84:87], v[92:95], v[40:43]
	v_mfma_f32_16x16x32_bf16 v[36:39], v[116:119], v[92:95], v[36:39]
	v_mfma_f32_16x16x32_bf16 v[32:35], v[120:123], v[92:95], v[32:35]
	s_waitcnt lgkmcnt(1)
	v_mfma_f32_16x16x32_bf16 v[28:31], v[80:83], v[88:91], v[28:31]
	v_mfma_f32_16x16x32_bf16 v[24:27], v[84:87], v[88:91], v[24:27]
	v_mfma_f32_16x16x32_bf16 v[16:19], v[116:119], v[88:91], v[16:19]
	v_mfma_f32_16x16x32_bf16 v[12:15], v[120:123], v[88:91], v[12:15]
	s_waitcnt lgkmcnt(0)
	v_mfma_f32_16x16x32_bf16 v[8:11], v[80:83], v[144:147], v[8:11]
	v_mfma_f32_16x16x32_bf16 v[20:23], v[84:87], v[144:147], v[20:23]
	v_mfma_f32_16x16x32_bf16 v[4:7], v[116:119], v[144:147], v[4:7]
	v_mfma_f32_16x16x32_bf16 v[0:3], v[120:123], v[144:147], v[0:3]
	s_setprio 0
	s_cmp_eq_u32 s0, 17
	s_cbranch_scc0 .LBB0_376
	s_mov_b32 s21, 0
	s_movk_i32 s20, 0x780
	s_mov_b32 s1, 15
	s_cmp_lt_u32 s22, 8
	s_cbranch_scc0 .Lnq_skip
	v_mul_f32_e32 v64, v48, v48
	v_fmac_f32_e32 v64, v49, v49
	v_fmac_f32_e32 v64, v50, v50
	v_fmac_f32_e32 v64, v51, v51
	v_fmac_f32_e32 v64, v52, v52
	v_fmac_f32_e32 v64, v53, v53
	v_fmac_f32_e32 v64, v54, v54
	v_fmac_f32_e32 v64, v55, v55
	v_fmac_f32_e32 v64, v56, v56
	v_fmac_f32_e32 v64, v57, v57
	v_fmac_f32_e32 v64, v58, v58
	v_fmac_f32_e32 v64, v59, v59
	v_fmac_f32_e32 v64, v60, v60
	v_fmac_f32_e32 v64, v61, v61
	v_fmac_f32_e32 v64, v62, v62
	v_fmac_f32_e32 v64, v63, v63
	v_mul_f32_e32 v65, v32, v32
	v_fmac_f32_e32 v65, v33, v33
	v_fmac_f32_e32 v65, v34, v34
	v_fmac_f32_e32 v65, v35, v35
	v_fmac_f32_e32 v65, v36, v36
	v_fmac_f32_e32 v65, v37, v37
	v_fmac_f32_e32 v65, v38, v38
	v_fmac_f32_e32 v65, v39, v39
	v_fmac_f32_e32 v65, v40, v40
	v_fmac_f32_e32 v65, v41, v41
	v_fmac_f32_e32 v65, v42, v42
	v_fmac_f32_e32 v65, v43, v43
	v_fmac_f32_e32 v65, v44, v44
	v_fmac_f32_e32 v65, v45, v45
	v_fmac_f32_e32 v65, v46, v46
	v_fmac_f32_e32 v65, v47, v47
	v_mul_f32_e32 v66, v12, v12
	v_fmac_f32_e32 v66, v13, v13
	v_fmac_f32_e32 v66, v14, v14
	v_fmac_f32_e32 v66, v15, v15
	v_fmac_f32_e32 v66, v16, v16
	v_fmac_f32_e32 v66, v17, v17
	v_fmac_f32_e32 v66, v18, v18
	v_fmac_f32_e32 v66, v19, v19
	v_fmac_f32_e32 v66, v24, v24
	v_fmac_f32_e32 v66, v25, v25
	v_fmac_f32_e32 v66, v26, v26
	v_fmac_f32_e32 v66, v27, v27
	v_fmac_f32_e32 v66, v28, v28
	v_fmac_f32_e32 v66, v29, v29
	v_fmac_f32_e32 v66, v30, v30
	v_fmac_f32_e32 v66, v31, v31
	v_mul_f32_e32 v67, v0, v0
	v_fmac_f32_e32 v67, v1, v1
	v_fmac_f32_e32 v67, v2, v2
	v_fmac_f32_e32 v67, v3, v3
	v_fmac_f32_e32 v67, v4, v4
	v_fmac_f32_e32 v67, v5, v5
	v_fmac_f32_e32 v67, v6, v6
	v_fmac_f32_e32 v67, v7, v7
	v_fmac_f32_e32 v67, v8, v8
	v_fmac_f32_e32 v67, v9, v9
	v_fmac_f32_e32 v67, v10, v10
	v_fmac_f32_e32 v67, v11, v11
	v_fmac_f32_e32 v67, v20, v20
	v_fmac_f32_e32 v67, v21, v21
	v_fmac_f32_e32 v67, v22, v22
	v_fmac_f32_e32 v67, v23, v23
	v_mov_b32_e32 v68, v64
	s_nop 1
	v_permlane16_swap_b32_e32 v68, v64
	v_add_f32_e32 v64, v64, v68
	v_mov_b32_e32 v68, v64
	s_nop 1
	v_permlane32_swap_b32_e32 v68, v64
	v_add_f32_e32 v64, v64, v68
	v_mov_b32_e32 v68, v65
	s_nop 1
	v_permlane16_swap_b32_e32 v68, v65
	v_add_f32_e32 v65, v65, v68
	v_mov_b32_e32 v68, v65
	s_nop 1
	v_permlane32_swap_b32_e32 v68, v65
	v_add_f32_e32 v65, v65, v68
	v_mov_b32_e32 v68, v66
	s_nop 1
	v_permlane16_swap_b32_e32 v68, v66
	v_add_f32_e32 v66, v66, v68
	v_mov_b32_e32 v68, v66
	s_nop 1
	v_permlane32_swap_b32_e32 v68, v66
	v_add_f32_e32 v66, v66, v68
	v_mov_b32_e32 v68, v67
	s_nop 1
	v_permlane16_swap_b32_e32 v68, v67
	v_add_f32_e32 v67, v67, v68
	v_mov_b32_e32 v68, v67
	s_nop 1
	v_permlane32_swap_b32_e32 v68, v67
	v_add_f32_e32 v67, v67, v68
	v_lshl_or_b32 v69, v96, 6, v98
	v_lshlrev_b32_e32 v69, 2, v69
	ds_read_b32 v70, v69 offset:32768
	ds_read_b32 v71, v69 offset:32832
	ds_read_b32 v72, v69 offset:32896
	ds_read_b32 v73, v69 offset:32960
	v_readlane_b32 s98, v165, 2
	v_readlane_b32 s99, v165, 3
	v_readlane_b32 s32, v167, 36
	s_waitcnt lgkmcnt(0)
	v_mul_f32_e32 v70, v70, v70
	v_mul_f32_e32 v64, v64, v70
	v_mul_f32_e32 v71, v71, v71
	v_mul_f32_e32 v65, v65, v71
	v_mul_f32_e32 v72, v72, v72
	v_mul_f32_e32 v66, v66, v72
	v_mul_f32_e32 v73, v73, v73
	v_mul_f32_e32 v67, v67, v73
	v_max3_f32 v64, v64, v65, v66
	v_max_f32_e32 v64, v64, v67
	s_mul_i32 s32, s32, 0xc00
	s_add_i32 s32, s32, 32
	v_mov_b32_e32 v69, s32
	s_and_b32 s32, s2, 7
	v_lshl_add_u32 v69, s32, 7, v69
	v_max_f32_dpp v64, v64, v64 row_ror:8 row_mask:0xf bank_mask:0xf
	s_lshr_b32 s32, s22, 2
	v_lshl_add_u32 v69, s32, 10, v69
	v_max_f32_dpp v64, v64, v64 row_ror:4 row_mask:0xf bank_mask:0xf
	s_and_b32 s32, s22, 3
	v_lshl_add_u32 v69, s32, 3, v69
	v_max_f32_dpp v64, v64, v64 quad_perm:[2,3,0,1] row_mask:0xf bank_mask:0xf
	v_lshl_add_u32 v69, v97, 2, v69
	v_cmp_eq_u32_e32 vcc, 0, v130
	v_max_f32_dpp v64, v64, v64 quad_perm:[1,0,3,2] row_mask:0xf bank_mask:0xf
	s_and_saveexec_b64 s[36:37], vcc
	global_atomic_umax v69, v64, s[98:99]
	s_or_b64 exec, exec, s[36:37]
